# w_in phase tail converts 256 fewer weight items (its idle workgroups were finishing about 3 us after the last tile)
# speedup vs baseline: 1.0150x; 1.0042x over previous
; __global__ void __launch_bounds__(NTHREADS, 2) fwd_kernel(Params P) {
;     ...
;         for (int it = gw; it < IT_TOTAL; it += NGW) {
;             int r = it; const float* W; bf16_t* WT; int N, ldk, mode = 0; const float* fg = nullptr; const float* fb = nullptr; float* cs = nullptr;
;             if (r < IT_GU) { W = P.in[I_WIN]; WT = WIN; N = NZ; ldk = D; fg = P.in[I_LN1G]; fb = P.in[I_LN1B]; cs = CSUM; }
;             else if ((r -= IT_GU) < IT_SQ) { W = P.in[I_WKV]; WT = WKV; N = D; ldk = D; }
;             else if ((r -= IT_SQ) < 3 * IT_BR) { const int k = r / IT_BR; r -= k * IT_BR; W = P.in[I_WBR] + (size_t)k * BW * D; WT = WBR + (size_t)k * D * BW; N = D; ldk = BW; }
;             else if ((r -= 3 * IT_BR) < IT_SQ) { W = P.in[I_WOUT]; WT = WOUT; N = D; ldk = D; }
;             else if ((r -= IT_SQ) < IT_GU) { W = P.in[I_GU2]; WT = WGU2; N = NZ; ldk = D; mode = 1; fg = P.in[I_LN2G]; fb = P.in[I_LN2B]; cs = CSUM + 2 * NZ; }
;             else if ((r -= IT_GU) < IT_DN) { W = P.in[I_DN2]; WT = WD2; N = D; ldk = FF; }
;             else if ((r -= IT_DN) < 16 * IT_LR) { const int m = r / IT_LR; r -= m * IT_LR; const int k = m >> 1, x = m & 1;
;                 W = (x ? P.in[I_LWX] : P.in[I_LWA]) + (size_t)k * 128 * 128; WT = WLRU + (size_t)k * 256 * 128 + x * 128 * 128; N = 128; ldk = 128; }
;             else if ((r -= 16 * IT_LR) < IT_DN) { W = P.in[I_DN1]; WT = WD1; N = D; ldk = FF; }
;             else { r -= IT_DN; W = P.in[I_GU1]; WT = WGU1; N = NZ; ldk = D; mode = 1; }
;             const int nblk = N / 32, kb = r / nblk, nb = r % nblk, n0 = 32 * nb;
;             int dr = n0;
;             if (mode == 1) dr = (n0 < FF) ? (n0 / 128) * 256 + (n0 % 128) : ((n0 - FF) / 128) * 256 + 128 + ((n0 - FF) % 128);
;             transpose_item(W, N, WT, ldk, 64 * kb, n0, dr, scr, lane, fg, fb, cs);
.Lcv_exit:
	s_cmp_lg_u32 s100, 0
	s_cbranch_scc1 .Lcv_d1
	s_mov_b32 s100, 1
	s_mov_b32 s98, 0x73ff
	v_readlane_b32 s99, v255, 13
	s_lshl_b32 s101, s34, 3
	s_nop 3
	s_add_i32 s99, s99, s101
	s_add_i32 s99, s99, 0x400
	s_and_b32 s99, s99, 0x7ff
	s_add_i32 s30, s99, 0x5700
	s_branch .Lcv_entry

; __global__ void __launch_bounds__(NTHREADS, 2) fwd_kernel(Params P) {
;     ...
;         for (int it = gw; it < IT_TOTAL; it += NGW) {
;             int r = it; const float* W; bf16_t* WT; int N, ldk, mode = 0; const float* fg = nullptr; const float* fb = nullptr; float* cs = nullptr;
;             if (r < IT_GU) { W = P.in[I_WIN]; WT = WIN; N = NZ; ldk = D; fg = P.in[I_LN1G]; fb = P.in[I_LN1B]; cs = CSUM; }
;             else if ((r -= IT_GU) < IT_SQ) { W = P.in[I_WKV]; WT = WKV; N = D; ldk = D; }
;             else if ((r -= IT_SQ) < 3 * IT_BR) { const int k = r / IT_BR; r -= k * IT_BR; W = P.in[I_WBR] + (size_t)k * BW * D; WT = WBR + (size_t)k * D * BW; N = D; ldk = BW; }
;             else if ((r -= 3 * IT_BR) < IT_SQ) { W = P.in[I_WOUT]; WT = WOUT; N = D; ldk = D; }
;             else if ((r -= IT_SQ) < IT_GU) { W = P.in[I_GU2]; WT = WGU2; N = NZ; ldk = D; mode = 1; fg = P.in[I_LN2G]; fb = P.in[I_LN2B]; cs = CSUM + 2 * NZ; }
;             else if ((r -= IT_GU) < IT_DN) { W = P.in[I_DN2]; WT = WD2; N = D; ldk = FF; }
;             else if ((r -= IT_DN) < 16 * IT_LR) { const int m = r / IT_LR; r -= m * IT_LR; const int k = m >> 1, x = m & 1;
;                 W = (x ? P.in[I_LWX] : P.in[I_LWA]) + (size_t)k * 128 * 128; WT = WLRU + (size_t)k * 256 * 128 + x * 128 * 128; N = 128; ldk = 128; }
;             else if ((r -= 16 * IT_LR) < IT_DN) { W = P.in[I_DN1]; WT = WD1; N = D; ldk = FF; }
;             else { r -= IT_DN; W = P.in[I_GU1]; WT = WGU1; N = NZ; ldk = D; mode = 1; }
;             const int nblk = N / 32, kb = r / nblk, nb = r % nblk, n0 = 32 * nb;
;             int dr = n0;
;             if (mode == 1) dr = (n0 < FF) ? (n0 / 128) * 256 + (n0 % 128) : ((n0 - FF) / 128) * 256 + 128 + ((n0 - FF) % 128);
;             transpose_item(W, N, WT, ldk, 64 * kb, n0, dr, scr, lane, fg, fb, cs);
.LBB0_506:
	s_cmp_lt_u32 s34, 220
	s_cbranch_scc1 .Lcv_skip_p4
	v_writelane_b32 v252, s0, 0
	v_writelane_b32 v252, s1, 1
	v_writelane_b32 v252, s2, 2
	v_writelane_b32 v252, s3, 3
	v_writelane_b32 v252, s4, 4
	v_writelane_b32 v252, s5, 5
	v_writelane_b32 v252, s6, 6
	v_writelane_b32 v252, s7, 7
	v_writelane_b32 v252, s8, 8
	v_writelane_b32 v252, s9, 9
	v_writelane_b32 v252, s10, 10
	v_writelane_b32 v252, s11, 11
	v_writelane_b32 v252, s12, 12
	v_writelane_b32 v252, s13, 13
	v_writelane_b32 v252, s14, 14
	v_writelane_b32 v252, s15, 15
	v_writelane_b32 v252, s16, 16
	v_writelane_b32 v252, s17, 17
	v_writelane_b32 v252, s18, 18
	v_writelane_b32 v252, s19, 19
	v_writelane_b32 v252, s20, 20
	v_writelane_b32 v252, s21, 21
	v_writelane_b32 v252, s22, 22
	v_writelane_b32 v252, s23, 23
	v_writelane_b32 v252, s24, 24
	v_writelane_b32 v252, s25, 25
	v_writelane_b32 v252, s26, 26
	v_writelane_b32 v252, s27, 27
	v_writelane_b32 v252, s28, 28
	v_writelane_b32 v252, s29, 29
	v_writelane_b32 v252, s30, 30
	v_writelane_b32 v252, s31, 31
	v_writelane_b32 v252, s32, 32
	v_writelane_b32 v252, s33, 33
	v_writelane_b32 v252, s34, 34
	v_writelane_b32 v252, s35, 35
	v_writelane_b32 v252, s36, 36
	v_writelane_b32 v252, s37, 37
	v_writelane_b32 v252, s38, 38
	v_writelane_b32 v252, s39, 39
	v_writelane_b32 v252, s40, 40
	v_writelane_b32 v252, s41, 41
	v_writelane_b32 v252, s42, 42
	v_writelane_b32 v252, s43, 43
	v_writelane_b32 v252, s44, 44
	v_writelane_b32 v252, s45, 45
	v_writelane_b32 v252, s46, 46
	v_writelane_b32 v252, s47, 47
	v_writelane_b32 v252, s48, 48
	v_writelane_b32 v252, s49, 49
	v_writelane_b32 v252, s50, 50
	v_writelane_b32 v252, s51, 51
	v_writelane_b32 v252, s52, 52
	v_writelane_b32 v252, s53, 53
	v_writelane_b32 v252, s54, 54
	v_writelane_b32 v252, s55, 55
	v_writelane_b32 v252, s56, 56
	v_writelane_b32 v252, s57, 57
	v_writelane_b32 v252, s58, 58
	v_writelane_b32 v252, s59, 59
	v_writelane_b32 v252, s60, 60
	v_writelane_b32 v252, s61, 61
	v_writelane_b32 v252, s62, 62
	v_writelane_b32 v252, s63, 63
	v_writelane_b32 v253, s64, 0
	v_writelane_b32 v253, s65, 1
	v_writelane_b32 v253, s66, 2
	v_writelane_b32 v253, s67, 3
	v_writelane_b32 v253, s68, 4
	v_writelane_b32 v253, s69, 5
	v_writelane_b32 v253, s70, 6
	v_writelane_b32 v253, s71, 7
	v_writelane_b32 v253, s72, 8
	v_writelane_b32 v253, s73, 9
	v_writelane_b32 v253, s74, 10
	v_writelane_b32 v253, s75, 11
	v_writelane_b32 v253, s76, 12
	v_writelane_b32 v253, s77, 13
	v_writelane_b32 v253, s78, 14
	v_writelane_b32 v253, s79, 15
	v_writelane_b32 v253, s80, 16
	v_writelane_b32 v253, s81, 17
	v_writelane_b32 v253, s82, 18
	v_writelane_b32 v253, s83, 19
	v_writelane_b32 v253, s84, 20
	v_writelane_b32 v253, s85, 21
	v_writelane_b32 v253, s86, 22
	v_writelane_b32 v253, s87, 23
	v_writelane_b32 v253, s88, 24
	v_writelane_b32 v253, s89, 25
	v_writelane_b32 v253, s90, 26
	v_writelane_b32 v253, s91, 27
	v_writelane_b32 v253, s92, 28
	v_writelane_b32 v253, s93, 29
	v_writelane_b32 v253, s94, 30
	v_writelane_b32 v253, s95, 31
	v_writelane_b32 v253, s96, 32
	v_writelane_b32 v253, s97, 33
	s_mov_b32 s100, 4
	s_mov_b32 s98, 0x56ff
	v_and_b32_e32 v237, 63, v178
	v_readlane_b32 s99, v255, 13
	v_readfirstlane_b32 s37, v178
	s_nop 4
	s_sub_i32 s101, s34, 220
	s_lshl_b32 s101, s101, 3
	s_add_i32 s99, s99, s101
	s_add_i32 s30, s99, 0x4800
	s_movk_i32 s86, 288
	s_branch .Lcv_entry
